# P5 epilogue: out stores write whole 128-byte lines (column halves exchanged between lane halves by DPP row shifts)
# speedup vs baseline: 1.0116x; 1.0116x over previous
;     __device__ __forceinline__ void operator()(const f32x4 (&acc)[2][2][4][2], const Unit& u, int wr, int wc, int fr, int fq) const {
;         const size_t row0 = (size_t)u.pm * BM + wr * 64 + fr; const int col0 = u.pn * BM + wc * 32 + 4 * fq; const float* gp = gate + (size_t)(u.pm >> 4) * 3072 + col0;
;         f32x4 gv[2][2];
; #pragma unroll
;         for (int bj = 0; bj < 2; ++bj)
; #pragma unroll
;             for (int n = 0; n < 2; ++n) gv[bj][n] = *(const f32x4*)(gp + bj * HALF + n * 16);
; #pragma unroll
;         for (int ai = 0; ai < 2; ++ai) {
;             f32x4 xv[4][2][2];
; #pragma unroll
;             for (int m = 0; m < 4; ++m) { const size_t off = (row0 + ai * HALF + m * 16) * 1024 + col0;
; #pragma unroll
;                 for (int bj = 0; bj < 2; ++bj)
; #pragma unroll
;                     for (int n = 0; n < 2; ++n) xv[m][bj][n] = *(const f32x4*)(x + off + bj * HALF + n * 16); }
;             asm volatile("" ::: "memory");
; #pragma unroll
;             for (int m = 0; m < 4; ++m) { const size_t off = (row0 + ai * HALF + m * 16) * 1024 + col0;
; #pragma unroll
;                 for (int bj = 0; bj < 2; ++bj)
; #pragma unroll
;                     for (int n = 0; n < 2; ++n) *(f32x4*)(out + off + bj * HALF + n * 16) = xv[m][bj][n] + gv[bj][n] * acc[ai][bj][m][n]; }
.LBB0_588:
	s_ashr_i32 s23, s30, 4
	s_ashr_i32 s31, s30, 31
	v_lshl_or_b32 v128, s61, 8, v163
	s_mul_hi_i32 s25, s23, 0x3000
	s_mulk_i32 s23, 0x3000
	s_add_u32 s34, s50, s23
	v_ashrrev_i32_e32 v129, 31, v128
	s_addc_u32 s35, s51, s25
	v_lshlrev_b64 v[232:233], 2, v[128:129]
	v_mbcnt_lo_u32_b32 v246, -1, 0
	v_mbcnt_hi_u32_b32 v246, -1, v246
	v_bfe_u32 v246, v246, 3, 1
	v_mul_i32_i24_e32 v246, 0xffff8040, v246
	v_ashrrev_i32_e32 v247, 31, v246
	v_lshl_add_u64 v[246:247], v[232:233], 0, v[246:247]
	v_mov_b32_e32 v248, 0x8000
	v_mov_b32_e32 v249, 0
	s_lshl_b64 s[30:31], s[30:31], 20
	v_lshl_add_u64 v[158:159], s[4:5], 0, v[232:233]
	v_lshl_add_u64 v[234:235], s[30:31], 0, v[148:149]
	v_lshl_add_u64 v[128:129], s[34:35], 0, v[232:233]
	v_lshl_add_u64 v[160:161], v[158:159], 0, v[234:235]
	global_load_dwordx4 v[168:171], v[160:161], off
	global_load_dwordx4 v[140:143], v[128:129], off
	global_load_dwordx4 v[136:139], v[128:129], off offset:64
	global_load_dwordx4 v[172:175], v[160:161], off offset:64
	global_load_dwordx4 v[176:179], v[160:161], off offset:512
	global_load_dwordx4 v[132:135], v[128:129], off offset:512
	s_nop 0
	global_load_dwordx4 v[128:131], v[128:129], off offset:576
	s_nop 0
	global_load_dwordx4 v[180:183], v[160:161], off offset:576
	v_or_b32_e32 v236, 0x10000, v234
	v_mov_b32_e32 v237, v235
	v_or_b32_e32 v238, 0x20000, v234
	v_mov_b32_e32 v239, v235
	v_or_b32_e32 v240, 0x30000, v234
	v_mov_b32_e32 v241, v235
	v_lshl_add_u64 v[196:197], v[158:159], 0, v[236:237]
	v_lshl_add_u64 v[212:213], v[158:159], 0, v[238:239]
	v_lshl_add_u64 v[158:159], v[158:159], 0, v[240:241]
	global_load_dwordx4 v[184:187], v[196:197], off
	global_load_dwordx4 v[188:191], v[196:197], off offset:64
	global_load_dwordx4 v[192:195], v[196:197], off offset:512
	s_nop 0
	global_load_dwordx4 v[196:199], v[196:197], off offset:576
	s_nop 0
	global_load_dwordx4 v[200:203], v[212:213], off
	global_load_dwordx4 v[204:207], v[212:213], off offset:64
	global_load_dwordx4 v[208:211], v[212:213], off offset:512
	s_nop 0
	global_load_dwordx4 v[212:215], v[212:213], off offset:576
	s_nop 0
	global_load_dwordx4 v[216:219], v[158:159], off
	global_load_dwordx4 v[220:223], v[158:159], off offset:64
	global_load_dwordx4 v[224:227], v[158:159], off offset:512
	global_load_dwordx4 v[228:231], v[158:159], off offset:576
	v_lshl_add_u64 v[158:159], s[6:7], 0, v[234:235]
	v_lshl_add_u64 v[158:159], v[158:159], 0, v[246:247]
	v_lshl_add_u64 v[234:235], s[6:7], 0, v[236:237]
	v_lshl_add_u64 v[236:237], s[6:7], 0, v[238:239]
	v_lshl_add_u64 v[238:239], s[6:7], 0, v[240:241]
	v_lshl_add_u64 v[234:235], v[234:235], 0, v[246:247]
	v_lshl_add_u64 v[236:237], v[236:237], 0, v[246:247]
	s_waitcnt vmcnt(0)
	v_pk_fma_f32 v[126:127], v[126:127], v[142:143], v[170:171]
	v_pk_fma_f32 v[124:125], v[124:125], v[140:141], v[168:169]
	v_pk_fma_f32 v[122:123], v[122:123], v[138:139], v[174:175]
	v_pk_fma_f32 v[120:121], v[120:121], v[136:137], v[172:173]
	v_pk_fma_f32 v[106:107], v[106:107], v[134:135], v[178:179]
	v_pk_fma_f32 v[104:105], v[104:105], v[132:133], v[176:177]
	v_pk_fma_f32 v[98:99], v[98:99], v[130:131], v[182:183]
	v_pk_fma_f32 v[96:97], v[96:97], v[128:129], v[180:181]
	s_nop 1
	v_mov_b32_e32 v252, v124
	v_mov_b32_e32 v253, v125
	v_mov_b32_e32 v254, v126
	v_mov_b32_e32 v255, v127
	v_mov_b32_dpp v124, v120 row_shr:8 row_mask:0xf bank_mask:0xc
	v_mov_b32_dpp v125, v121 row_shr:8 row_mask:0xf bank_mask:0xc
	v_mov_b32_dpp v126, v122 row_shr:8 row_mask:0xf bank_mask:0xc
	v_mov_b32_dpp v127, v123 row_shr:8 row_mask:0xf bank_mask:0xc
	v_mov_b32_dpp v120, v252 row_shl:8 row_mask:0xf bank_mask:0x3
	v_mov_b32_dpp v121, v253 row_shl:8 row_mask:0xf bank_mask:0x3
	v_mov_b32_dpp v122, v254 row_shl:8 row_mask:0xf bank_mask:0x3
	v_mov_b32_dpp v123, v255 row_shl:8 row_mask:0xf bank_mask:0x3
	v_lshl_add_u64 v[250:251], v[158:159], 0, v[248:249]
	global_store_dwordx4 v[158:159], v[124:127], off
	global_store_dwordx4 v[250:251], v[120:123], off
	s_nop 1
	v_mov_b32_e32 v252, v104
	v_mov_b32_e32 v253, v105
	v_mov_b32_e32 v254, v106
	v_mov_b32_e32 v255, v107
	v_mov_b32_dpp v104, v96 row_shr:8 row_mask:0xf bank_mask:0xc
	v_mov_b32_dpp v105, v97 row_shr:8 row_mask:0xf bank_mask:0xc
	v_mov_b32_dpp v106, v98 row_shr:8 row_mask:0xf bank_mask:0xc
	v_mov_b32_dpp v107, v99 row_shr:8 row_mask:0xf bank_mask:0xc
	v_mov_b32_dpp v96, v252 row_shl:8 row_mask:0xf bank_mask:0x3
	v_mov_b32_dpp v97, v253 row_shl:8 row_mask:0xf bank_mask:0x3
	v_mov_b32_dpp v98, v254 row_shl:8 row_mask:0xf bank_mask:0x3
	v_mov_b32_dpp v99, v255 row_shl:8 row_mask:0xf bank_mask:0x3
	v_lshl_add_u64 v[250:251], v[158:159], 0, v[248:249]
	global_store_dwordx4 v[158:159], v[104:107], off offset:512
	global_store_dwordx4 v[250:251], v[96:99], off offset:512
	v_lshl_add_u64 v[124:125], v[160:161], 0, s[20:21]
	v_lshl_add_u64 v[170:171], v[158:159], 0, s[16:17]
	v_pk_fma_f32 v[98:99], v[118:119], v[142:143], v[186:187]
	v_pk_fma_f32 v[96:97], v[116:117], v[140:141], v[184:185]
	v_pk_fma_f32 v[106:107], v[114:115], v[138:139], v[190:191]
	v_pk_fma_f32 v[80:81], v[80:81], v[132:133], v[208:209]
	v_pk_fma_f32 v[104:105], v[112:113], v[136:137], v[188:189]
	v_pk_fma_f32 v[90:91], v[90:91], v[134:135], v[194:195]
	v_pk_fma_f32 v[88:89], v[88:89], v[132:133], v[192:193]
	v_pk_fma_f32 v[86:87], v[86:87], v[130:131], v[198:199]
	v_pk_fma_f32 v[84:85], v[84:85], v[128:129], v[196:197]
	v_pk_fma_f32 v[110:111], v[110:111], v[142:143], v[202:203]
	v_pk_fma_f32 v[108:109], v[108:109], v[140:141], v[200:201]
	v_pk_fma_f32 v[102:103], v[102:103], v[138:139], v[206:207]
	v_pk_fma_f32 v[100:101], v[100:101], v[136:137], v[204:205]
;     __device__ __forceinline__ void operator()(const f32x4 (&acc)[2][2][4][2], const Unit& u, int wr, int wc, int fr, int fq) const {
;     ...
;         for (int ai = 0; ai < 2; ++ai) {
;             f32x4 xv[4][2][2];
; #pragma unroll
;             for (int m = 0; m < 4; ++m) { const size_t off = (row0 + ai * HALF + m * 16) * 1024 + col0;
; #pragma unroll
;                 for (int bj = 0; bj < 2; ++bj)
; #pragma unroll
;                     for (int n = 0; n < 2; ++n) xv[m][bj][n] = *(const f32x4*)(x + off + bj * HALF + n * 16); }
;             asm volatile("" ::: "memory");
; #pragma unroll
;             for (int m = 0; m < 4; ++m) { const size_t off = (row0 + ai * HALF + m * 16) * 1024 + col0;
; #pragma unroll
;                 for (int bj = 0; bj < 2; ++bj)
; #pragma unroll
;                     for (int n = 0; n < 2; ++n) *(f32x4*)(out + off + bj * HALF + n * 16) = xv[m][bj][n] + gv[bj][n] * acc[ai][bj][m][n]; }
	v_pk_fma_f32 v[82:83], v[82:83], v[134:135], v[210:211]
	v_pk_fma_f32 v[74:75], v[74:75], v[130:131], v[214:215]
	v_pk_fma_f32 v[72:73], v[72:73], v[128:129], v[212:213]
	s_nop 1
	v_mov_b32_e32 v252, v96
	v_mov_b32_e32 v253, v97
	v_mov_b32_e32 v254, v98
	v_mov_b32_e32 v255, v99
	v_mov_b32_dpp v96, v104 row_shr:8 row_mask:0xf bank_mask:0xc
	v_mov_b32_dpp v97, v105 row_shr:8 row_mask:0xf bank_mask:0xc
	v_mov_b32_dpp v98, v106 row_shr:8 row_mask:0xf bank_mask:0xc
	v_mov_b32_dpp v99, v107 row_shr:8 row_mask:0xf bank_mask:0xc
	v_mov_b32_dpp v104, v252 row_shl:8 row_mask:0xf bank_mask:0x3
	v_mov_b32_dpp v105, v253 row_shl:8 row_mask:0xf bank_mask:0x3
	v_mov_b32_dpp v106, v254 row_shl:8 row_mask:0xf bank_mask:0x3
	v_mov_b32_dpp v107, v255 row_shl:8 row_mask:0xf bank_mask:0x3
	v_lshl_add_u64 v[250:251], v[234:235], 0, v[248:249]
	global_store_dwordx4 v[234:235], v[96:99], off
	global_store_dwordx4 v[250:251], v[104:107], off
	s_nop 1
	v_mov_b32_e32 v252, v88
	v_mov_b32_e32 v253, v89
	v_mov_b32_e32 v254, v90
	v_mov_b32_e32 v255, v91
	v_mov_b32_dpp v88, v84 row_shr:8 row_mask:0xf bank_mask:0xc
	v_mov_b32_dpp v89, v85 row_shr:8 row_mask:0xf bank_mask:0xc
	v_mov_b32_dpp v90, v86 row_shr:8 row_mask:0xf bank_mask:0xc
	v_mov_b32_dpp v91, v87 row_shr:8 row_mask:0xf bank_mask:0xc
	v_mov_b32_dpp v84, v252 row_shl:8 row_mask:0xf bank_mask:0x3
	v_mov_b32_dpp v85, v253 row_shl:8 row_mask:0xf bank_mask:0x3
	v_mov_b32_dpp v86, v254 row_shl:8 row_mask:0xf bank_mask:0x3
	v_mov_b32_dpp v87, v255 row_shl:8 row_mask:0xf bank_mask:0x3
	v_lshl_add_u64 v[250:251], v[234:235], 0, v[248:249]
	global_store_dwordx4 v[234:235], v[88:91], off offset:512
	global_store_dwordx4 v[250:251], v[84:87], off offset:512
	s_nop 1
	v_mov_b32_e32 v252, v108
	v_mov_b32_e32 v253, v109
	v_mov_b32_e32 v254, v110
	v_mov_b32_e32 v255, v111
	v_mov_b32_dpp v108, v100 row_shr:8 row_mask:0xf bank_mask:0xc
	v_mov_b32_dpp v109, v101 row_shr:8 row_mask:0xf bank_mask:0xc
	v_mov_b32_dpp v110, v102 row_shr:8 row_mask:0xf bank_mask:0xc
	v_mov_b32_dpp v111, v103 row_shr:8 row_mask:0xf bank_mask:0xc
	v_mov_b32_dpp v100, v252 row_shl:8 row_mask:0xf bank_mask:0x3
	v_mov_b32_dpp v101, v253 row_shl:8 row_mask:0xf bank_mask:0x3
	v_mov_b32_dpp v102, v254 row_shl:8 row_mask:0xf bank_mask:0x3
	v_mov_b32_dpp v103, v255 row_shl:8 row_mask:0xf bank_mask:0x3
	v_lshl_add_u64 v[250:251], v[236:237], 0, v[248:249]
	global_store_dwordx4 v[236:237], v[108:111], off
	global_store_dwordx4 v[250:251], v[100:103], off
	s_nop 1
	v_mov_b32_e32 v252, v80
	v_mov_b32_e32 v253, v81
	v_mov_b32_e32 v254, v82
	v_mov_b32_e32 v255, v83
	v_mov_b32_dpp v80, v72 row_shr:8 row_mask:0xf bank_mask:0xc
	v_mov_b32_dpp v81, v73 row_shr:8 row_mask:0xf bank_mask:0xc
	v_mov_b32_dpp v82, v74 row_shr:8 row_mask:0xf bank_mask:0xc
	v_mov_b32_dpp v83, v75 row_shr:8 row_mask:0xf bank_mask:0xc
	v_mov_b32_dpp v72, v252 row_shl:8 row_mask:0xf bank_mask:0x3
	v_mov_b32_dpp v73, v253 row_shl:8 row_mask:0xf bank_mask:0x3
	v_mov_b32_dpp v74, v254 row_shl:8 row_mask:0xf bank_mask:0x3
	v_mov_b32_dpp v75, v255 row_shl:8 row_mask:0xf bank_mask:0x3
	v_lshl_add_u64 v[250:251], v[236:237], 0, v[248:249]
	global_store_dwordx4 v[236:237], v[80:83], off offset:512
	global_store_dwordx4 v[250:251], v[72:75], off offset:512
	v_pk_fma_f32 v[66:67], v[66:67], v[130:131], v[230:231]
	v_lshl_add_u64 v[80:81], v[238:239], 0, v[246:247]
	v_pk_fma_f32 v[64:65], v[64:65], v[128:129], v[228:229]
	v_pk_fma_f32 v[94:95], v[94:95], v[142:143], v[218:219]
	v_pk_fma_f32 v[92:93], v[92:93], v[140:141], v[216:217]
	v_add_co_u32_e32 v242, vcc, s57, v160
	v_pk_fma_f32 v[74:75], v[78:79], v[138:139], v[222:223]
	v_pk_fma_f32 v[72:73], v[76:77], v[136:137], v[220:221]
	v_pk_fma_f32 v[70:71], v[70:71], v[134:135], v[226:227]
	v_pk_fma_f32 v[68:69], v[68:69], v[132:133], v[224:225]
	v_addc_co_u32_e32 v243, vcc, 0, v161, vcc
	s_nop 1
	v_mov_b32_e32 v252, v92
	v_mov_b32_e32 v253, v93
	v_mov_b32_e32 v254, v94
	v_mov_b32_e32 v255, v95
	v_mov_b32_dpp v92, v72 row_shr:8 row_mask:0xf bank_mask:0xc
	v_mov_b32_dpp v93, v73 row_shr:8 row_mask:0xf bank_mask:0xc
	v_mov_b32_dpp v94, v74 row_shr:8 row_mask:0xf bank_mask:0xc
	v_mov_b32_dpp v95, v75 row_shr:8 row_mask:0xf bank_mask:0xc
	v_mov_b32_dpp v72, v252 row_shl:8 row_mask:0xf bank_mask:0x3
	v_mov_b32_dpp v73, v253 row_shl:8 row_mask:0xf bank_mask:0x3
	v_mov_b32_dpp v74, v254 row_shl:8 row_mask:0xf bank_mask:0x3
	v_mov_b32_dpp v75, v255 row_shl:8 row_mask:0xf bank_mask:0x3
	v_lshl_add_u64 v[250:251], v[80:81], 0, v[248:249]
	global_store_dwordx4 v[80:81], v[92:95], off
	global_store_dwordx4 v[250:251], v[72:75], off
	s_nop 1
	v_mov_b32_e32 v252, v68
	v_mov_b32_e32 v253, v69
	v_mov_b32_e32 v254, v70
	v_mov_b32_e32 v255, v71
	v_mov_b32_dpp v68, v64 row_shr:8 row_mask:0xf bank_mask:0xc
	v_mov_b32_dpp v69, v65 row_shr:8 row_mask:0xf bank_mask:0xc
	v_mov_b32_dpp v70, v66 row_shr:8 row_mask:0xf bank_mask:0xc
	v_mov_b32_dpp v71, v67 row_shr:8 row_mask:0xf bank_mask:0xc
	v_mov_b32_dpp v64, v252 row_shl:8 row_mask:0xf bank_mask:0x3
	v_mov_b32_dpp v65, v253 row_shl:8 row_mask:0xf bank_mask:0x3
	v_mov_b32_dpp v66, v254 row_shl:8 row_mask:0xf bank_mask:0x3
	v_mov_b32_dpp v67, v255 row_shl:8 row_mask:0xf bank_mask:0x3
	v_lshl_add_u64 v[250:251], v[80:81], 0, v[248:249]
	global_store_dwordx4 v[80:81], v[68:71], off offset:512
	global_store_dwordx4 v[250:251], v[64:67], off offset:512
	v_add_co_u32_e32 v80, vcc, s58, v160
	v_lshl_add_u64 v[76:77], v[160:161], 0, s[14:15]
	s_nop 0
	v_addc_co_u32_e32 v81, vcc, 0, v161, vcc
	v_lshl_add_u64 v[92:93], v[160:161], 0, s[16:17]
	v_add_co_u32_e32 v96, vcc, s59, v160
	global_load_dwordx4 v[64:67], v[242:243], off
	s_nop 0
	global_load_dwordx4 v[68:71], v[76:77], off offset:64
	global_load_dwordx4 v[72:75], v[76:77], off offset:512
	s_nop 0
	global_load_dwordx4 v[76:79], v[76:77], off offset:576
	v_addc_co_u32_e32 v97, vcc, 0, v161, vcc
	global_load_dwordx4 v[80:83], v[80:81], off
	s_nop 0
	global_load_dwordx4 v[84:87], v[92:93], off offset:64
	global_load_dwordx4 v[88:91], v[92:93], off offset:512
	s_nop 0
	global_load_dwordx4 v[92:95], v[92:93], off offset:576
	v_lshl_add_u64 v[108:109], v[160:161], 0, s[18:19]
	global_load_dwordx4 v[96:99], v[96:97], off
	v_add_co_u32_e32 v112, vcc, s60, v160
	global_load_dwordx4 v[100:103], v[108:109], off offset:64
	global_load_dwordx4 v[104:107], v[108:109], off offset:512
	s_nop 0
	global_load_dwordx4 v[108:111], v[108:109], off offset:576
	v_addc_co_u32_e32 v113, vcc, 0, v161, vcc
	global_load_dwordx4 v[112:115], v[112:113], off
	s_nop 0
	global_load_dwordx4 v[116:119], v[124:125], off offset:64
	global_load_dwordx4 v[120:123], v[124:125], off offset:512
	s_nop 0
	global_load_dwordx4 v[124:127], v[124:125], off offset:576
	v_lshl_add_u64 v[160:161], v[158:159], 0, s[14:15]
	s_nop 0
	s_waitcnt vmcnt(15)
;     __device__ __forceinline__ void operator()(const f32x4 (&acc)[2][2][4][2], const Unit& u, int wr, int wc, int fr, int fq) const {
;     ...
;             for (int m = 0; m < 4; ++m) { const size_t off = (row0 + ai * HALF + m * 16) * 1024 + col0;
; #pragma unroll
;                 for (int bj = 0; bj < 2; ++bj)
; #pragma unroll
;                     for (int n = 0; n < 2; ++n) xv[m][bj][n] = *(const f32x4*)(x + off + bj * HALF + n * 16); }
;             asm volatile("" ::: "memory");
; #pragma unroll
;             for (int m = 0; m < 4; ++m) { const size_t off = (row0 + ai * HALF + m * 16) * 1024 + col0;
; #pragma unroll
;                 for (int bj = 0; bj < 2; ++bj)
; #pragma unroll
;                     for (int n = 0; n < 2; ++n) *(f32x4*)(out + off + bj * HALF + n * 16) = xv[m][bj][n] + gv[bj][n] * acc[ai][bj][m][n]; }
	v_pk_fma_f32 v[62:63], v[62:63], v[142:143], v[66:67]
	v_pk_fma_f32 v[60:61], v[60:61], v[140:141], v[64:65]
	s_waitcnt vmcnt(14)
	v_pk_fma_f32 v[58:59], v[58:59], v[138:139], v[70:71]
	v_pk_fma_f32 v[56:57], v[56:57], v[136:137], v[68:69]
	s_waitcnt vmcnt(13)
	v_pk_fma_f32 v[46:47], v[46:47], v[134:135], v[74:75]
	s_waitcnt vmcnt(8)
	v_pk_fma_f32 v[30:31], v[30:31], v[130:131], v[94:95]
	v_pk_fma_f32 v[44:45], v[44:45], v[132:133], v[72:73]
	v_pk_fma_f32 v[42:43], v[42:43], v[130:131], v[78:79]
	v_pk_fma_f32 v[40:41], v[40:41], v[128:129], v[76:77]
	v_pk_fma_f32 v[54:55], v[54:55], v[142:143], v[82:83]
	v_pk_fma_f32 v[52:53], v[52:53], v[140:141], v[80:81]
	v_pk_fma_f32 v[50:51], v[50:51], v[138:139], v[86:87]
	v_pk_fma_f32 v[48:49], v[48:49], v[136:137], v[84:85]
	v_pk_fma_f32 v[38:39], v[38:39], v[134:135], v[90:91]
	v_pk_fma_f32 v[36:37], v[36:37], v[132:133], v[88:89]
	v_pk_fma_f32 v[28:29], v[28:29], v[128:129], v[92:93]
	s_nop 1
	v_mov_b32_e32 v252, v60
	v_mov_b32_e32 v253, v61
	v_mov_b32_e32 v254, v62
	v_mov_b32_e32 v255, v63
	v_mov_b32_dpp v60, v56 row_shr:8 row_mask:0xf bank_mask:0xc
	v_mov_b32_dpp v61, v57 row_shr:8 row_mask:0xf bank_mask:0xc
	v_mov_b32_dpp v62, v58 row_shr:8 row_mask:0xf bank_mask:0xc
	v_mov_b32_dpp v63, v59 row_shr:8 row_mask:0xf bank_mask:0xc
	v_mov_b32_dpp v56, v252 row_shl:8 row_mask:0xf bank_mask:0x3
	v_mov_b32_dpp v57, v253 row_shl:8 row_mask:0xf bank_mask:0x3
	v_mov_b32_dpp v58, v254 row_shl:8 row_mask:0xf bank_mask:0x3
	v_mov_b32_dpp v59, v255 row_shl:8 row_mask:0xf bank_mask:0x3
	v_lshl_add_u64 v[250:251], v[160:161], 0, v[248:249]
	global_store_dwordx4 v[160:161], v[60:63], off
	global_store_dwordx4 v[250:251], v[56:59], off
	s_nop 1
	v_mov_b32_e32 v252, v44
	v_mov_b32_e32 v253, v45
	v_mov_b32_e32 v254, v46
	v_mov_b32_e32 v255, v47
	v_mov_b32_dpp v44, v40 row_shr:8 row_mask:0xf bank_mask:0xc
	v_mov_b32_dpp v45, v41 row_shr:8 row_mask:0xf bank_mask:0xc
	v_mov_b32_dpp v46, v42 row_shr:8 row_mask:0xf bank_mask:0xc
	v_mov_b32_dpp v47, v43 row_shr:8 row_mask:0xf bank_mask:0xc
	v_mov_b32_dpp v40, v252 row_shl:8 row_mask:0xf bank_mask:0x3
	v_mov_b32_dpp v41, v253 row_shl:8 row_mask:0xf bank_mask:0x3
	v_mov_b32_dpp v42, v254 row_shl:8 row_mask:0xf bank_mask:0x3
	v_mov_b32_dpp v43, v255 row_shl:8 row_mask:0xf bank_mask:0x3
	v_lshl_add_u64 v[250:251], v[160:161], 0, v[248:249]
	global_store_dwordx4 v[160:161], v[44:47], off offset:512
	global_store_dwordx4 v[250:251], v[40:43], off offset:512
	s_nop 1
	v_mov_b32_e32 v252, v52
	v_mov_b32_e32 v253, v53
	v_mov_b32_e32 v254, v54
	v_mov_b32_e32 v255, v55
	v_mov_b32_dpp v52, v48 row_shr:8 row_mask:0xf bank_mask:0xc
	v_mov_b32_dpp v53, v49 row_shr:8 row_mask:0xf bank_mask:0xc
	v_mov_b32_dpp v54, v50 row_shr:8 row_mask:0xf bank_mask:0xc
	v_mov_b32_dpp v55, v51 row_shr:8 row_mask:0xf bank_mask:0xc
	v_mov_b32_dpp v48, v252 row_shl:8 row_mask:0xf bank_mask:0x3
	v_mov_b32_dpp v49, v253 row_shl:8 row_mask:0xf bank_mask:0x3
	v_mov_b32_dpp v50, v254 row_shl:8 row_mask:0xf bank_mask:0x3
	v_mov_b32_dpp v51, v255 row_shl:8 row_mask:0xf bank_mask:0x3
	v_lshl_add_u64 v[250:251], v[170:171], 0, v[248:249]
	global_store_dwordx4 v[170:171], v[52:55], off
	global_store_dwordx4 v[250:251], v[48:51], off
	s_nop 1
	v_mov_b32_e32 v252, v36
	v_mov_b32_e32 v253, v37
	v_mov_b32_e32 v254, v38
	v_mov_b32_e32 v255, v39
	v_mov_b32_dpp v36, v28 row_shr:8 row_mask:0xf bank_mask:0xc
	v_mov_b32_dpp v37, v29 row_shr:8 row_mask:0xf bank_mask:0xc
	v_mov_b32_dpp v38, v30 row_shr:8 row_mask:0xf bank_mask:0xc
	v_mov_b32_dpp v39, v31 row_shr:8 row_mask:0xf bank_mask:0xc
	v_mov_b32_dpp v28, v252 row_shl:8 row_mask:0xf bank_mask:0x3
	v_mov_b32_dpp v29, v253 row_shl:8 row_mask:0xf bank_mask:0x3
	v_mov_b32_dpp v30, v254 row_shl:8 row_mask:0xf bank_mask:0x3
	v_mov_b32_dpp v31, v255 row_shl:8 row_mask:0xf bank_mask:0x3
	v_lshl_add_u64 v[250:251], v[170:171], 0, v[248:249]
	global_store_dwordx4 v[170:171], v[36:39], off offset:512
	global_store_dwordx4 v[250:251], v[28:31], off offset:512
	s_waitcnt vmcnt(13)
;     __device__ __forceinline__ void operator()(const f32x4 (&acc)[2][2][4][2], const Unit& u, int wr, int wc, int fr, int fq) const {
;     ...
;             for (int m = 0; m < 4; ++m) { const size_t off = (row0 + ai * HALF + m * 16) * 1024 + col0;
; #pragma unroll
;                 for (int bj = 0; bj < 2; ++bj)
; #pragma unroll
;                     for (int n = 0; n < 2; ++n) xv[m][bj][n] = *(const f32x4*)(x + off + bj * HALF + n * 16); }
;             asm volatile("" ::: "memory");
; #pragma unroll
;             for (int m = 0; m < 4; ++m) { const size_t off = (row0 + ai * HALF + m * 16) * 1024 + col0;
; #pragma unroll
;                 for (int bj = 0; bj < 2; ++bj)
; #pragma unroll
;                     for (int n = 0; n < 2; ++n) *(f32x4*)(out + off + bj * HALF + n * 16) = xv[m][bj][n] + gv[bj][n] * acc[ai][bj][m][n]; }
;             asm volatile("" ::: "memory"); }
	v_pk_fma_f32 v[18:19], v[18:19], v[134:135], v[106:107]
	v_pk_fma_f32 v[16:17], v[16:17], v[132:133], v[104:105]
	v_pk_fma_f32 v[30:31], v[34:35], v[142:143], v[98:99]
	v_pk_fma_f32 v[28:29], v[32:33], v[140:141], v[96:97]
	v_lshl_add_u64 v[32:33], v[158:159], 0, s[18:19]
	s_waitcnt vmcnt(12)
	v_pk_fma_f32 v[14:15], v[14:15], v[130:131], v[110:111]
	v_pk_fma_f32 v[12:13], v[12:13], v[128:129], v[108:109]
	v_pk_fma_f32 v[26:27], v[26:27], v[138:139], v[102:103]
	v_pk_fma_f32 v[24:25], v[24:25], v[136:137], v[100:101]
	s_nop 1
	v_mov_b32_e32 v252, v16
	v_mov_b32_e32 v253, v17
	v_mov_b32_e32 v254, v18
	v_mov_b32_e32 v255, v19
	v_mov_b32_dpp v16, v12 row_shr:8 row_mask:0xf bank_mask:0xc
	v_mov_b32_dpp v17, v13 row_shr:8 row_mask:0xf bank_mask:0xc
	v_mov_b32_dpp v18, v14 row_shr:8 row_mask:0xf bank_mask:0xc
	v_mov_b32_dpp v19, v15 row_shr:8 row_mask:0xf bank_mask:0xc
	v_mov_b32_dpp v12, v252 row_shl:8 row_mask:0xf bank_mask:0x3
	v_mov_b32_dpp v13, v253 row_shl:8 row_mask:0xf bank_mask:0x3
	v_mov_b32_dpp v14, v254 row_shl:8 row_mask:0xf bank_mask:0x3
	v_mov_b32_dpp v15, v255 row_shl:8 row_mask:0xf bank_mask:0x3
	v_lshl_add_u64 v[250:251], v[32:33], 0, v[248:249]
	global_store_dwordx4 v[32:33], v[16:19], off offset:512
	global_store_dwordx4 v[250:251], v[12:15], off offset:512
	v_lshl_add_u64 v[244:245], v[158:159], 0, s[20:21]
	s_waitcnt vmcnt(13)
	v_pk_fma_f32 v[14:15], v[22:23], v[142:143], v[114:115]
	v_pk_fma_f32 v[12:13], v[20:21], v[140:141], v[112:113]
	s_waitcnt vmcnt(12)
	v_pk_fma_f32 v[10:11], v[10:11], v[138:139], v[118:119]
	v_pk_fma_f32 v[8:9], v[8:9], v[136:137], v[116:117]
	s_waitcnt vmcnt(11)
	v_pk_fma_f32 v[6:7], v[6:7], v[134:135], v[122:123]
	v_pk_fma_f32 v[4:5], v[4:5], v[132:133], v[120:121]
	s_waitcnt vmcnt(10)
	v_pk_fma_f32 v[2:3], v[2:3], v[130:131], v[126:127]
	v_pk_fma_f32 v[0:1], v[0:1], v[128:129], v[124:125]
	s_nop 1
	v_mov_b32_e32 v252, v28
	v_mov_b32_e32 v253, v29
	v_mov_b32_e32 v254, v30
	v_mov_b32_e32 v255, v31
	v_mov_b32_dpp v28, v24 row_shr:8 row_mask:0xf bank_mask:0xc
	v_mov_b32_dpp v29, v25 row_shr:8 row_mask:0xf bank_mask:0xc
	v_mov_b32_dpp v30, v26 row_shr:8 row_mask:0xf bank_mask:0xc
	v_mov_b32_dpp v31, v27 row_shr:8 row_mask:0xf bank_mask:0xc
	v_mov_b32_dpp v24, v252 row_shl:8 row_mask:0xf bank_mask:0x3
	v_mov_b32_dpp v25, v253 row_shl:8 row_mask:0xf bank_mask:0x3
	v_mov_b32_dpp v26, v254 row_shl:8 row_mask:0xf bank_mask:0x3
	v_mov_b32_dpp v27, v255 row_shl:8 row_mask:0xf bank_mask:0x3
	v_lshl_add_u64 v[250:251], v[32:33], 0, v[248:249]
	global_store_dwordx4 v[32:33], v[28:31], off
	global_store_dwordx4 v[250:251], v[24:27], off
	s_nop 1
	v_mov_b32_e32 v252, v12
	v_mov_b32_e32 v253, v13
	v_mov_b32_e32 v254, v14
	v_mov_b32_e32 v255, v15
	v_mov_b32_dpp v12, v8 row_shr:8 row_mask:0xf bank_mask:0xc
	v_mov_b32_dpp v13, v9 row_shr:8 row_mask:0xf bank_mask:0xc
	v_mov_b32_dpp v14, v10 row_shr:8 row_mask:0xf bank_mask:0xc
	v_mov_b32_dpp v15, v11 row_shr:8 row_mask:0xf bank_mask:0xc
	v_mov_b32_dpp v8, v252 row_shl:8 row_mask:0xf bank_mask:0x3
	v_mov_b32_dpp v9, v253 row_shl:8 row_mask:0xf bank_mask:0x3
	v_mov_b32_dpp v10, v254 row_shl:8 row_mask:0xf bank_mask:0x3
	v_mov_b32_dpp v11, v255 row_shl:8 row_mask:0xf bank_mask:0x3
	v_lshl_add_u64 v[250:251], v[244:245], 0, v[248:249]
	global_store_dwordx4 v[244:245], v[12:15], off
	global_store_dwordx4 v[250:251], v[8:11], off
	s_nop 1
	v_mov_b32_e32 v252, v4
	v_mov_b32_e32 v253, v5
	v_mov_b32_e32 v254, v6
	v_mov_b32_e32 v255, v7
	v_mov_b32_dpp v4, v0 row_shr:8 row_mask:0xf bank_mask:0xc
	v_mov_b32_dpp v5, v1 row_shr:8 row_mask:0xf bank_mask:0xc
	v_mov_b32_dpp v6, v2 row_shr:8 row_mask:0xf bank_mask:0xc
	v_mov_b32_dpp v7, v3 row_shr:8 row_mask:0xf bank_mask:0xc
	v_mov_b32_dpp v0, v252 row_shl:8 row_mask:0xf bank_mask:0x3
	v_mov_b32_dpp v1, v253 row_shl:8 row_mask:0xf bank_mask:0x3
	v_mov_b32_dpp v2, v254 row_shl:8 row_mask:0xf bank_mask:0x3
	v_mov_b32_dpp v3, v255 row_shl:8 row_mask:0xf bank_mask:0x3
	v_lshl_add_u64 v[250:251], v[244:245], 0, v[248:249]
	global_store_dwordx4 v[244:245], v[4:7], off offset:512
	global_store_dwordx4 v[250:251], v[0:3], off offset:512
	s_andn2_b64 vcc, exec, s[0:1]
	s_mov_b64 s[0:1], -1
	s_cbranch_vccnz .LBB0_577
	s_andn2_b64 vcc, exec, s[8:9]
	s_cbranch_vccnz .LBB0_576
	s_barrier
	s_branch .LBB0_576
